# v19 plus retention-state phase tile body regenerated: V^T B-fragment reads batched per 16-token step and next step K^T reads prefetched (no lgkmcnt(0) before every MFMA)
# baseline (speedup 1.0000x reference)
; __device__ __forceinline__ void state_unit(LAS unsigned char* lds, const Args& a, int b, int hh, int dir, int eh, int wid, int lane) {
;     ...
;     for (int t = 0; t < NT; ++t) {
;         if (t + 1 < NT) asm volatile("s_waitcnt vmcnt(6) lgkmcnt(0)" ::: "memory"); else asm volatile("s_waitcnt vmcnt(0) lgkmcnt(0)" ::: "memory");
;         __builtin_amdgcn_s_barrier();
;         asm volatile("" ::: "memory");
;         if (t + 2 < NT) ST_TILE_ISSUE(t + 2);
;         if (t >= 4 && (t - 4) % TPC == 0) {
;             const int wi = (t - 4) / TPC; bf16_t* S = ST + (size_t)(dir ? NRCH + (NRCH - 1 - wi) : wi) * 65536;
; #pragma unroll
;             for (int d = 0; d < 4; ++d)
; #pragma unroll
;                 for (int i = 0; i < 16; ++i) { S[(size_t)(32 * wid + (i & 3) + 8 * (i >> 2) + 4 * h) * 256 + 128 * eh + 32 * d + r] = (bf16_t)(cvtpk(acc[d][i], 0.f) & 0xffffu); acc[d][i] *= gch; }
;         }
;         const LAS unsigned char* Kt = lds + (t % 3) * 49152; const LAS unsigned char* Vt = Kt + 32768;
;         const int p0 = (t < 4 ? 64 * t : 64 * ((t - 4) % TPC)) + 8 * h, last = t < 4 ? 255 : RCH - 1;
; #pragma unroll
;         for (int s = 0; s < 4; ++s) {
;             const LAS unsigned char* kb = Kt + (16 * s + 8 * h + tq) * 512 + lanec + (((wid ^ tq) & 3) << 6) + (wid >> 2) * 256;
;             const s16x4 klo = vtr(kb), khi = vtr(kb + 4 * 512);
;             const int p = p0 + 16 * s;
;             float w = __builtin_amdgcn_exp2f(lg2 * (float)(dir ? p : last - p));
;             const u32x2 lw = __builtin_bit_cast(u32x2, klo), hw = __builtin_bit_cast(u32x2, khi);
;             float kv[8] = {bflo(lw.x), bfhi(lw.x), bflo(lw.y), bfhi(lw.y), bflo(hw.x), bfhi(hw.x), bflo(hw.y), bfhi(hw.y)};
; #pragma unroll
;             for (int j = 0; j < 8; ++j) { kv[j] *= w; w *= m; }
;             u32x4 pw; pw.x = cvtpk(kv[0], kv[1]); pw.y = cvtpk(kv[2], kv[3]); pw.z = cvtpk(kv[4], kv[5]); pw.w = cvtpk(kv[6], kv[7]);
;             const bf16x8 af = __builtin_bit_cast(bf16x8, pw);
;             const LAS unsigned char* vb = Vt + (16 * s + 8 * h + tq) * 256 + lanec;
; #pragma unroll
;             for (int d = 0; d < 4; ++d) {
;                 const LAS unsigned char* vp = vb + (((d ^ tq) & 3) << 6);
;                 const s16x4 lo = vtr(vp), hi = vtr(vp + 4 * 256);
;                 acc[d] = MFMA32(af, __builtin_shufflevector(lo, hi, 0, 1, 2, 3, 4, 5, 6, 7), acc[d]); }
.LBB0_579:
	s_mul_hi_u32 s40, s78, 0xaaaaaaab
	s_lshr_b32 s40, s40, 1
	s_mul_i32 s40, s40, 0xfffdc000
	s_add_i32 s46, s76, 0xfffffe80
	v_add_u32_e32 v187, s40, v140
	v_add_u32_e32 v188, s40, v142
	v_add_u32_e32 v199, s40, v143
	v_add_u32_e32 v200, s40, v144
	v_add_u32_e32 v209, s40, v145
	v_add_u32_e32 v210, s40, v146
	v_add_u32_e32 v66, s40, v147
	v_add_u32_e32 v64, s40, v148
	v_add_u32_e32 v75, s40, v149
	v_add_u32_e32 v123, s40, v150
	v_add_u32_e32 v125, s40, v151
	v_add_u32_e32 v127, s40, v152
	v_add_u32_e32 v183, s40, v153
	v_add_u32_e32 v184, s40, v154
	v_add_u32_e32 v185, s40, v155
	v_add_u32_e32 v186, s40, v156
	v_add_u32_e32 v189, s40, v157
	v_add_u32_e32 v190, s40, v158
	v_add_u32_e32 v191, s40, v159
	v_add_u32_e32 v192, s40, v160
	v_add_u32_e32 v193, s40, v161
	v_add_u32_e32 v194, s40, v162
	v_add_u32_e32 v196, s40, v163
	v_add_u32_e32 v197, s40, v164
	v_add_u32_e32 v201, s40, v165
	v_add_u32_e32 v202, s40, v166
	v_add_u32_e32 v203, s40, v167
	v_add_u32_e32 v204, s40, v168
	v_add_u32_e32 v205, s40, v169
	v_add_u32_e32 v206, s40, v170
	v_add_u32_e32 v207, s40, v171
	v_add_u32_e32 v208, s40, v172
	v_add_u32_e32 v211, s40, v173
	v_add_u32_e32 v220, s40, v174
	v_add_u32_e32 v221, s40, v175
	v_add_u32_e32 v222, s40, v178
	v_add_u32_e32 v223, s40, v179
	v_add_u32_e32 v224, s40, v180
	v_add_u32_e32 v225, s40, v181
	v_add_u32_e32 v226, s40, v182
	s_and_b32 s40, s46, 0x1c0
	s_xor_b32 s47, s40, 0x100
	s_cmp_lt_u32 s79, 4
	s_movk_i32 s40, 0x1ff
	s_cselect_b32 s46, s46, s47
	s_cselect_b32 s40, 0xff, s40
	v_add_u32_e32 v195, s46, v139
	v_add3_u32 v64, v64, v141, s77
	v_add3_u32 v66, v66, v141, s77
	ds_read_b64_tr_b16 v[64:65], v64
	ds_read_b64_tr_b16 v[66:67], v66
	v_add3_u32 v226, v226, v141, s77
	v_add3_u32 v225, v225, v141, s77
	v_add3_u32 v224, v224, v141, s77
	v_add3_u32 v223, v223, v141, s77
	v_add3_u32 v222, v222, v141, s77
	v_add3_u32 v221, v221, v141, s77
	v_add3_u32 v220, v220, v141, s77
	v_add3_u32 v211, v211, v141, s77
	ds_read_b64_tr_b16 v[228:229], v226
	ds_read_b64_tr_b16 v[230:231], v225
	ds_read_b64_tr_b16 v[232:233], v224
	ds_read_b64_tr_b16 v[234:235], v223
	ds_read_b64_tr_b16 v[236:237], v222
	ds_read_b64_tr_b16 v[238:239], v221
	ds_read_b64_tr_b16 v[216:217], v220
	ds_read_b64_tr_b16 v[218:219], v211
	v_add3_u32 v210, v210, v141, s77
	v_add3_u32 v209, v209, v141, s77
	ds_read_b64_tr_b16 v[220:221], v210
	ds_read_b64_tr_b16 v[222:223], v209
	v_sub_u32_e32 v240, s40, v195
	v_cndmask_b32_e64 v227, v195, v240, s[0:1]
	v_cvt_f32_i32_e32 v227, v227
	v_mul_f32_e32 v227, v137, v227
	v_exp_f32_e32 v212, v227
	s_waitcnt lgkmcnt(10)
	v_lshlrev_b32_e32 v214, 16, v64
	v_and_b32_e32 v215, 0xffff0000, v64
	v_mul_f32_e32 v213, v138, v212
	v_pk_mul_f32 v[214:215], v[212:213], v[214:215]
	v_cvt_pk_bf16_f32 v64, v214, v215
	v_lshlrev_b32_e32 v214, 16, v65
	v_and_b32_e32 v215, 0xffff0000, v65
	v_mul_f32_e32 v212, v138, v213
	v_mul_f32_e32 v213, v138, v212
	v_pk_mul_f32 v[214:215], v[212:213], v[214:215]
	v_cvt_pk_bf16_f32 v65, v214, v215
	v_lshlrev_b32_e32 v214, 16, v66
	v_and_b32_e32 v215, 0xffff0000, v66
	v_mul_f32_e32 v212, v138, v213
	v_mul_f32_e32 v213, v138, v212
	v_pk_mul_f32 v[214:215], v[212:213], v[214:215]
	v_cvt_pk_bf16_f32 v66, v214, v215
	v_lshlrev_b32_e32 v214, 16, v67
	v_and_b32_e32 v215, 0xffff0000, v67
	v_mul_f32_e32 v212, v138, v213
	v_mul_f32_e32 v213, v138, v212
	v_pk_mul_f32 v[214:215], v[212:213], v[214:215]
	v_cvt_pk_bf16_f32 v67, v214, v215
	s_nop 1
	s_waitcnt lgkmcnt(8)
	v_mfma_f32_32x32x16_bf16 v[48:63], v[64:67], v[228:231], v[48:63]
	s_waitcnt lgkmcnt(6)
	v_mfma_f32_32x32x16_bf16 v[32:47], v[64:67], v[232:235], v[32:47]
	s_waitcnt lgkmcnt(4)
	v_mfma_f32_32x32x16_bf16 v[16:31], v[64:67], v[236:239], v[16:31]
	s_waitcnt lgkmcnt(2)
	v_mfma_f32_32x32x16_bf16 v[0:15], v[64:67], v[216:219], v[0:15]
	v_add3_u32 v208, v208, v141, s77
	v_add3_u32 v207, v207, v141, s77
	v_add3_u32 v206, v206, v141, s77
	v_add3_u32 v205, v205, v141, s77
	v_add3_u32 v204, v204, v141, s77
	v_add3_u32 v203, v203, v141, s77
	v_add3_u32 v202, v202, v141, s77
	v_add3_u32 v201, v201, v141, s77
	ds_read_b64_tr_b16 v[228:229], v208
	ds_read_b64_tr_b16 v[230:231], v207
	ds_read_b64_tr_b16 v[232:233], v206
	ds_read_b64_tr_b16 v[234:235], v205
	ds_read_b64_tr_b16 v[236:237], v204
	ds_read_b64_tr_b16 v[238:239], v203
	ds_read_b64_tr_b16 v[216:217], v202
	ds_read_b64_tr_b16 v[218:219], v201
	v_add3_u32 v200, v200, v141, s77
	v_add3_u32 v199, v199, v141, s77
	ds_read_b64_tr_b16 v[204:205], v200
	ds_read_b64_tr_b16 v[206:207], v199
	v_add_u32_e32 v227, 16, v195
	v_sub_u32_e32 v240, s40, v227
	v_cndmask_b32_e64 v227, v227, v240, s[0:1]
	v_cvt_f32_i32_e32 v227, v227
	v_mul_f32_e32 v227, v137, v227
	v_exp_f32_e32 v212, v227
	s_waitcnt lgkmcnt(10)
; #define LAS __attribute__((address_space(3)))
; __device__ __forceinline__ unsigned cvtpk(float lo, float hi) { f32x2 v = {lo, hi}; bf16x2_t b = __builtin_convertvector(v, bf16x2_t); return __builtin_bit_cast(unsigned, b); }
; __device__ __forceinline__ float bflo(unsigned w) { return __uint_as_float(w << 16); }
; __device__ __forceinline__ float bfhi(unsigned w) { return __uint_as_float(w & 0xffff0000u); }
; __device__ __forceinline__ s16x4 vtr(const LAS unsigned char* p) { return __builtin_bit_cast(s16x4, __builtin_amdgcn_ds_read_tr16_b64_v4i16((LAS v4i16_t*)p)); }
; #define MFMA32(a, b, c) __builtin_amdgcn_mfma_f32_32x32x16_bf16((a), (b), (c), 0, 0, 0)
; __device__ __forceinline__ void state_unit(LAS unsigned char* lds, const Args& a, int b, int hh, int dir, int eh, int wid, int lane) {
;     ...
; #pragma unroll
;         for (int s = 0; s < 4; ++s) {
;             const LAS unsigned char* kb = Kt + (16 * s + 8 * h + tq) * 512 + lanec + (((wid ^ tq) & 3) << 6) + (wid >> 2) * 256;
;             const s16x4 klo = vtr(kb), khi = vtr(kb + 4 * 512);
;             const int p = p0 + 16 * s;
;             float w = __builtin_amdgcn_exp2f(lg2 * (float)(dir ? p : last - p));
;             const u32x2 lw = __builtin_bit_cast(u32x2, klo), hw = __builtin_bit_cast(u32x2, khi);
;             float kv[8] = {bflo(lw.x), bfhi(lw.x), bflo(lw.y), bfhi(lw.y), bflo(hw.x), bfhi(hw.x), bflo(hw.y), bfhi(hw.y)};
; #pragma unroll
;             for (int j = 0; j < 8; ++j) { kv[j] *= w; w *= m; }
;             u32x4 pw; pw.x = cvtpk(kv[0], kv[1]); pw.y = cvtpk(kv[2], kv[3]); pw.z = cvtpk(kv[4], kv[5]); pw.w = cvtpk(kv[6], kv[7]);
;             const bf16x8 af = __builtin_bit_cast(bf16x8, pw);
;             const LAS unsigned char* vb = Vt + (16 * s + 8 * h + tq) * 256 + lanec;
; #pragma unroll
;             for (int d = 0; d < 4; ++d) {
;                 const LAS unsigned char* vp = vb + (((d ^ tq) & 3) << 6);
;                 const s16x4 lo = vtr(vp), hi = vtr(vp + 4 * 256);
;                 acc[d] = MFMA32(af, __builtin_shufflevector(lo, hi, 0, 1, 2, 3, 4, 5, 6, 7), acc[d]); }
;         }
	v_lshlrev_b32_e32 v214, 16, v220
	v_and_b32_e32 v215, 0xffff0000, v220
	v_mul_f32_e32 v213, v138, v212
	v_pk_mul_f32 v[214:215], v[212:213], v[214:215]
	v_cvt_pk_bf16_f32 v220, v214, v215
	v_lshlrev_b32_e32 v214, 16, v221
	v_and_b32_e32 v215, 0xffff0000, v221
	v_mul_f32_e32 v212, v138, v213
	v_mul_f32_e32 v213, v138, v212
	v_pk_mul_f32 v[214:215], v[212:213], v[214:215]
	v_cvt_pk_bf16_f32 v221, v214, v215
	v_lshlrev_b32_e32 v214, 16, v222
	v_and_b32_e32 v215, 0xffff0000, v222
	v_mul_f32_e32 v212, v138, v213
	v_mul_f32_e32 v213, v138, v212
	v_pk_mul_f32 v[214:215], v[212:213], v[214:215]
	v_cvt_pk_bf16_f32 v222, v214, v215
	v_lshlrev_b32_e32 v214, 16, v223
	v_and_b32_e32 v215, 0xffff0000, v223
	v_mul_f32_e32 v212, v138, v213
	v_mul_f32_e32 v213, v138, v212
	v_pk_mul_f32 v[214:215], v[212:213], v[214:215]
	v_cvt_pk_bf16_f32 v223, v214, v215
	s_nop 1
	s_waitcnt lgkmcnt(8)
	v_mfma_f32_32x32x16_bf16 v[48:63], v[220:223], v[228:231], v[48:63]
	s_waitcnt lgkmcnt(6)
	v_mfma_f32_32x32x16_bf16 v[32:47], v[220:223], v[232:235], v[32:47]
	s_waitcnt lgkmcnt(4)
	v_mfma_f32_32x32x16_bf16 v[16:31], v[220:223], v[236:239], v[16:31]
	s_waitcnt lgkmcnt(2)
	v_mfma_f32_32x32x16_bf16 v[0:15], v[220:223], v[216:219], v[0:15]
	v_add3_u32 v197, v197, v141, s77
	v_add3_u32 v196, v196, v141, s77
	v_add3_u32 v194, v194, v141, s77
	v_add3_u32 v193, v193, v141, s77
	v_add3_u32 v192, v192, v141, s77
	v_add3_u32 v191, v191, v141, s77
	v_add3_u32 v190, v190, v141, s77
	v_add3_u32 v189, v189, v141, s77
	ds_read_b64_tr_b16 v[228:229], v197
	ds_read_b64_tr_b16 v[230:231], v196
	ds_read_b64_tr_b16 v[232:233], v194
	ds_read_b64_tr_b16 v[234:235], v193
	ds_read_b64_tr_b16 v[236:237], v192
	ds_read_b64_tr_b16 v[238:239], v191
	ds_read_b64_tr_b16 v[216:217], v190
	ds_read_b64_tr_b16 v[218:219], v189
	v_add3_u32 v188, v188, v141, s77
	v_add3_u32 v187, v187, v141, s77
	ds_read_b64_tr_b16 v[190:191], v188
	ds_read_b64_tr_b16 v[192:193], v187
	v_add_u32_e32 v227, 32, v195
	v_sub_u32_e32 v240, s40, v227
	v_cndmask_b32_e64 v227, v227, v240, s[0:1]
	v_cvt_f32_i32_e32 v227, v227
	v_mul_f32_e32 v227, v137, v227
	v_exp_f32_e32 v212, v227
	s_waitcnt lgkmcnt(10)
	v_lshlrev_b32_e32 v214, 16, v204
	v_and_b32_e32 v215, 0xffff0000, v204
	v_mul_f32_e32 v213, v138, v212
	v_pk_mul_f32 v[214:215], v[212:213], v[214:215]
	v_cvt_pk_bf16_f32 v204, v214, v215
	v_lshlrev_b32_e32 v214, 16, v205
	v_and_b32_e32 v215, 0xffff0000, v205
	v_mul_f32_e32 v212, v138, v213
	v_mul_f32_e32 v213, v138, v212
	v_pk_mul_f32 v[214:215], v[212:213], v[214:215]
	v_cvt_pk_bf16_f32 v205, v214, v215
	v_lshlrev_b32_e32 v214, 16, v206
	v_and_b32_e32 v215, 0xffff0000, v206
	v_mul_f32_e32 v212, v138, v213
	v_mul_f32_e32 v213, v138, v212
	v_pk_mul_f32 v[214:215], v[212:213], v[214:215]
	v_cvt_pk_bf16_f32 v206, v214, v215
	v_lshlrev_b32_e32 v214, 16, v207
	v_and_b32_e32 v215, 0xffff0000, v207
	v_mul_f32_e32 v212, v138, v213
	v_mul_f32_e32 v213, v138, v212
	v_pk_mul_f32 v[214:215], v[212:213], v[214:215]
	v_cvt_pk_bf16_f32 v207, v214, v215
	s_nop 1
	s_waitcnt lgkmcnt(8)
	v_mfma_f32_32x32x16_bf16 v[48:63], v[204:207], v[228:231], v[48:63]
	s_waitcnt lgkmcnt(6)
	v_mfma_f32_32x32x16_bf16 v[32:47], v[204:207], v[232:235], v[32:47]
	s_waitcnt lgkmcnt(4)
	v_mfma_f32_32x32x16_bf16 v[16:31], v[204:207], v[236:239], v[16:31]
	s_waitcnt lgkmcnt(2)
	v_mfma_f32_32x32x16_bf16 v[0:15], v[204:207], v[216:219], v[0:15]
	v_add3_u32 v186, v186, v141, s77
	v_add3_u32 v185, v185, v141, s77
	v_add3_u32 v184, v184, v141, s77
	v_add3_u32 v183, v183, v141, s77
	v_add3_u32 v127, v127, v141, s77
	v_add3_u32 v125, v125, v141, s77
	v_add3_u32 v123, v123, v141, s77
	v_add3_u32 v75, v75, v141, s77
	ds_read_b64_tr_b16 v[228:229], v186
	ds_read_b64_tr_b16 v[230:231], v185
	ds_read_b64_tr_b16 v[232:233], v184
	ds_read_b64_tr_b16 v[234:235], v183
	ds_read_b64_tr_b16 v[236:237], v127
	ds_read_b64_tr_b16 v[238:239], v125
	ds_read_b64_tr_b16 v[216:217], v123
	ds_read_b64_tr_b16 v[218:219], v75
	v_add_u32_e32 v227, 48, v195
	v_sub_u32_e32 v240, s40, v227
	v_cndmask_b32_e64 v227, v227, v240, s[0:1]
	v_cvt_f32_i32_e32 v227, v227
	v_mul_f32_e32 v227, v137, v227
	v_exp_f32_e32 v212, v227
	s_waitcnt lgkmcnt(8)
	v_lshlrev_b32_e32 v214, 16, v190
	v_and_b32_e32 v215, 0xffff0000, v190
	v_mul_f32_e32 v213, v138, v212
	v_pk_mul_f32 v[214:215], v[212:213], v[214:215]
	v_cvt_pk_bf16_f32 v190, v214, v215
	v_lshlrev_b32_e32 v214, 16, v191
	v_and_b32_e32 v215, 0xffff0000, v191
	v_mul_f32_e32 v212, v138, v213
	v_mul_f32_e32 v213, v138, v212
	v_pk_mul_f32 v[214:215], v[212:213], v[214:215]
	v_cvt_pk_bf16_f32 v191, v214, v215
	v_lshlrev_b32_e32 v214, 16, v192
	v_and_b32_e32 v215, 0xffff0000, v192
	v_mul_f32_e32 v212, v138, v213
	v_mul_f32_e32 v213, v138, v212
	v_pk_mul_f32 v[214:215], v[212:213], v[214:215]
	v_cvt_pk_bf16_f32 v192, v214, v215
	v_lshlrev_b32_e32 v214, 16, v193
	v_and_b32_e32 v215, 0xffff0000, v193
	v_mul_f32_e32 v212, v138, v213
	v_mul_f32_e32 v213, v138, v212
	v_pk_mul_f32 v[214:215], v[212:213], v[214:215]
	v_cvt_pk_bf16_f32 v193, v214, v215
	s_nop 1
	s_waitcnt lgkmcnt(6)
	v_mfma_f32_32x32x16_bf16 v[48:63], v[190:193], v[228:231], v[48:63]
	s_waitcnt lgkmcnt(4)
	v_mfma_f32_32x32x16_bf16 v[32:47], v[190:193], v[232:235], v[32:47]
	s_waitcnt lgkmcnt(2)
	v_mfma_f32_32x32x16_bf16 v[16:31], v[190:193], v[236:239], v[16:31]
	s_waitcnt lgkmcnt(0)
	v_mfma_f32_32x32x16_bf16 v[0:15], v[190:193], v[216:219], v[0:15]
	s_add_i32 s75, s75, 1
	s_add_i32 s76, s76, 64
	s_add_i32 s77, s77, 0xc000
	s_add_u32 s42, s42, 0x40000
	s_addc_u32 s43, s43, 0
	s_add_i32 s78, s78, 1
	s_cmp_lg_u32 s77, 0x150000
	s_cbranch_scc0 .LBB0_577
